# P0: input loads (w_in, x) marked non-temporal (nt) so the cold-start phase allocates fewer cache lines
# speedup vs baseline: 1.0146x; 1.0052x over previous
.LBB0_7:
	v_writelane_b32 v242, s4, 11
	s_load_dwordx16 s[4:19], s[0:1], 0x40
	s_lshr_b32 s1, s3, 6
	s_lshl_b32 s0, s2, 3
	s_add_i32 s56, s1, s0
	s_lshl_b32 s64, s74, 3
	s_waitcnt lgkmcnt(0)
	v_writelane_b32 v242, s4, 12
	v_and_b32_e32 v142, 63, v143
	s_nop 0
	v_writelane_b32 v242, s5, 13
	v_writelane_b32 v242, s6, 14
	v_writelane_b32 v242, s7, 15
	v_writelane_b32 v242, s8, 16
	v_writelane_b32 v242, s9, 17
	v_writelane_b32 v242, s10, 18
	v_writelane_b32 v242, s11, 19
	v_writelane_b32 v242, s12, 20
	v_writelane_b32 v242, s13, 21
	v_writelane_b32 v242, s14, 22
	v_writelane_b32 v242, s15, 23
	v_writelane_b32 v242, s16, 24
	v_writelane_b32 v242, s17, 25
	v_writelane_b32 v242, s18, 26
	v_writelane_b32 v242, s19, 27
	s_add_u32 s6, s70, 0x100000
	s_addc_u32 s7, s71, 0
	s_lshl_b32 s0, s1, 14
	v_writelane_b32 v242, s1, 28
	s_add_i32 s0, s0, 0
	v_writelane_b32 v242, s0, 29
	v_writelane_b32 v242, s65, 30
	v_writelane_b32 v242, s36, 31
	s_cmp_lt_i32 s72, 1
	s_cselect_b64 s[0:1], -1, 0
	v_writelane_b32 v242, s37, 32
	v_writelane_b32 v242, s38, 33
	v_writelane_b32 v242, s39, 34
	v_writelane_b32 v242, s40, 35
	v_writelane_b32 v242, s41, 36
	v_writelane_b32 v242, s42, 37
	v_writelane_b32 v242, s43, 38
	v_writelane_b32 v242, s44, 39
	v_writelane_b32 v242, s45, 40
	v_writelane_b32 v242, s46, 41
	s_cmp_gt_i32 s73, 0
	v_writelane_b32 v242, s47, 42
	s_cselect_b64 s[4:5], -1, 0
	v_writelane_b32 v242, s48, 43
	s_and_b64 s[4:5], s[0:1], s[4:5]
	v_writelane_b32 v242, s49, 44
	s_andn2_b64 vcc, exec, s[4:5]
	v_writelane_b32 v242, s50, 45
	v_writelane_b32 v242, s51, 46
	s_cbranch_vccnz .LBB0_22
	s_cmpk_lt_i32 s56, 0x2000
	s_cselect_b64 s[58:59], -1, 0
	s_cmpk_gt_i32 s56, 0x1fff
	s_cbranch_scc1 .LBB0_13
	s_ashr_i32 s0, s56, 31
	s_lshr_b32 s0, s0, 24
	s_add_i32 s0, s56, s0
	s_ashr_i32 s3, s0, 8
	s_and_b32 s0, s0, 0x7ffff00
	s_sub_i32 s0, s56, s0
	v_lshrrev_b32_e32 v1, 3, v142
	s_lshl_b32 s0, s0, 5
	s_ashr_i32 s1, s0, 31
	v_readlane_b32 s8, v242, 12
	v_lshl_or_b32 v28, s3, 6, v1
	s_lshl_b64 s[0:1], s[0:1], 2
	v_readlane_b32 s10, v242, 14
	v_ashrrev_i32_e32 v29, 31, v28
	v_readlane_b32 s11, v242, 15
	s_add_u32 s0, s10, s0
	v_and_b32_e32 v38, 7, v143
	v_lshlrev_b64 v[2:3], 15, v[28:29]
	v_or_b32_e32 v4, 8, v28
	v_or_b32_e32 v10, 16, v28
	v_or_b32_e32 v12, 24, v28
	v_or_b32_e32 v18, 32, v28
	v_or_b32_e32 v20, 40, v28
	v_or_b32_e32 v30, 48, v28
	v_or_b32_e32 v28, 56, v28
	s_addc_u32 s1, s11, s1
	v_lshlrev_b32_e32 v36, 4, v38
	v_mov_b32_e32 v37, 0
	v_ashrrev_i32_e32 v5, 31, v4
	v_ashrrev_i32_e32 v11, 31, v10
	v_ashrrev_i32_e32 v13, 31, v12
	v_ashrrev_i32_e32 v19, 31, v18
	v_ashrrev_i32_e32 v21, 31, v20
	v_ashrrev_i32_e32 v31, 31, v30
	v_ashrrev_i32_e32 v29, 31, v28
	v_lshl_add_u64 v[26:27], s[0:1], 0, v[36:37]
	v_lshlrev_b64 v[4:5], 15, v[4:5]
	v_lshlrev_b64 v[10:11], 15, v[10:11]
	v_lshlrev_b64 v[12:13], 15, v[12:13]
	v_lshlrev_b64 v[18:19], 15, v[18:19]
	v_lshlrev_b64 v[20:21], 15, v[20:21]
	v_lshlrev_b64 v[30:31], 15, v[30:31]
	v_lshlrev_b64 v[28:29], 15, v[28:29]
	v_lshl_add_u64 v[2:3], v[26:27], 0, v[2:3]
	v_lshl_add_u64 v[6:7], v[26:27], 0, v[4:5]
	v_lshl_add_u64 v[10:11], v[26:27], 0, v[10:11]
	v_lshl_add_u64 v[14:15], v[26:27], 0, v[12:13]
	v_lshl_add_u64 v[18:19], v[26:27], 0, v[18:19]
	v_lshl_add_u64 v[22:23], v[26:27], 0, v[20:21]
	v_lshl_add_u64 v[30:31], v[26:27], 0, v[30:31]
	v_lshl_add_u64 v[32:33], v[26:27], 0, v[28:29]
	global_load_dwordx4 v[2:5], v[2:3], off nt
	s_nop 0
	global_load_dwordx4 v[6:9], v[6:7], off nt
	s_nop 0
	global_load_dwordx4 v[10:13], v[10:11], off nt
	s_nop 0
	global_load_dwordx4 v[14:17], v[14:15], off nt
	s_nop 0
	global_load_dwordx4 v[18:21], v[18:19], off nt
	s_nop 0
	global_load_dwordx4 v[22:25], v[22:23], off nt
	s_nop 0
	global_load_dwordx4 v[26:29], v[30:31], off nt
	s_nop 0
	global_load_dwordx4 v[30:33], v[32:33], off nt
	v_readlane_b32 s0, v242, 29
	v_mul_u32_u24_e32 v38, 0x420, v38
	v_lshlrev_b32_e32 v40, 2, v1
	v_readlane_b32 s9, v242, 13
	v_add_u32_e32 v39, s0, v36
	v_add3_u32 v38, s0, v38, v40
	v_mul_u32_u24_e32 v40, 0x84, v1
	s_lshl_b32 s8, s64, 5
	v_lshl_add_u64 v[34:35], s[10:11], 0, v[36:37]
	v_lshl_add_u64 v[36:37], s[6:7], 0, v[36:37]
	s_lshl_b32 s3, s56, 5
	v_add_u32_e32 v39, v39, v40
	s_mov_b32 s9, s8
	v_mov_b32_e32 v40, v1
	s_mov_b32 s10, s56
	v_readlane_b32 s12, v242, 16
	v_readlane_b32 s13, v242, 17
	v_readlane_b32 s14, v242, 18
	v_readlane_b32 s15, v242, 19
	v_readlane_b32 s16, v242, 20
	v_readlane_b32 s17, v242, 21
	v_readlane_b32 s18, v242, 22
	v_readlane_b32 s19, v242, 23
	v_readlane_b32 s20, v242, 24
	v_readlane_b32 s21, v242, 25
	v_readlane_b32 s22, v242, 26
	v_readlane_b32 s23, v242, 27
	s_branch .LBB0_11

.LBB0_11:
	v_add_u32_e32 v41, 0x420, v39
	s_waitcnt vmcnt(7)
	ds_write2_b32 v39, v2, v3 offset1:1
	ds_write2_b32 v39, v4, v5 offset0:2 offset1:3
	s_waitcnt vmcnt(6)
	ds_write2_b32 v41, v6, v7 offset1:1
	v_add_u32_e32 v41, 0x428, v39
	ds_write2_b32 v41, v8, v9 offset1:1
	v_add_u32_e32 v41, 0x840, v39
	s_waitcnt vmcnt(5)
	ds_write2_b32 v41, v10, v11 offset1:1
	v_add_u32_e32 v41, 0x848, v39
	ds_write2_b32 v41, v12, v13 offset1:1
	v_add_u32_e32 v41, 0xc60, v39
	s_waitcnt vmcnt(4)
	ds_write2_b32 v41, v14, v15 offset1:1
	v_add_u32_e32 v41, 0xc68, v39
	ds_write2_b32 v41, v16, v17 offset1:1
	v_add_u32_e32 v41, 0x1080, v39
	s_waitcnt vmcnt(3)
	ds_write2_b32 v41, v18, v19 offset1:1
	v_add_u32_e32 v41, 0x1088, v39
	ds_write2_b32 v41, v20, v21 offset1:1
	v_add_u32_e32 v41, 0x14a0, v39
	s_waitcnt vmcnt(2)
	ds_write2_b32 v41, v22, v23 offset1:1
	v_add_u32_e32 v41, 0x14a8, v39
	ds_write2_b32 v41, v24, v25 offset1:1
	v_add_u32_e32 v41, 0x18c0, v39
	s_add_i32 s11, s10, s64
	s_waitcnt vmcnt(1)
	ds_write2_b32 v41, v26, v27 offset1:1
	v_add_u32_e32 v41, 0x18c8, v39
	s_cmpk_gt_i32 s11, 0x1fff
	ds_write2_b32 v41, v28, v29 offset1:1
	v_add_u32_e32 v41, 0x1ce0, v39
	s_cselect_b64 s[0:1], -1, 0
	s_waitcnt vmcnt(0)
	ds_write2_b32 v41, v30, v31 offset1:1
	v_add_u32_e32 v41, 0x1ce8, v39
	s_and_b64 vcc, exec, s[0:1]
	ds_write2_b32 v41, v32, v33 offset1:1
	s_cbranch_vccnz .LBB0_10
	s_ashr_i32 s12, s11, 31
	s_lshr_b32 s12, s12, 24
	s_add_i32 s12, s11, s12
	s_ashr_i32 s13, s12, 8
	v_lshl_or_b32 v26, s13, 6, v1
	s_add_i32 s12, s3, s9
	s_lshl_b32 s14, s13, 13
	v_ashrrev_i32_e32 v27, 31, v26
	s_sub_i32 s12, s12, s14
	v_lshlrev_b64 v[2:3], 15, v[26:27]
	v_or_b32_e32 v4, 8, v26
	v_or_b32_e32 v10, 16, v26
	v_or_b32_e32 v12, 24, v26
	v_or_b32_e32 v18, 32, v26
	v_or_b32_e32 v20, 40, v26
	v_or_b32_e32 v30, 48, v26
	v_or_b32_e32 v26, 56, v26
	s_ashr_i32 s13, s12, 31
	v_ashrrev_i32_e32 v5, 31, v4
	v_ashrrev_i32_e32 v11, 31, v10
	v_ashrrev_i32_e32 v13, 31, v12
	v_ashrrev_i32_e32 v19, 31, v18
	v_ashrrev_i32_e32 v21, 31, v20
	v_ashrrev_i32_e32 v31, 31, v30
	v_ashrrev_i32_e32 v27, 31, v26
	v_lshl_add_u64 v[28:29], s[12:13], 2, v[34:35]
	v_lshlrev_b64 v[4:5], 15, v[4:5]
	v_lshlrev_b64 v[10:11], 15, v[10:11]
	v_lshlrev_b64 v[12:13], 15, v[12:13]
	v_lshlrev_b64 v[18:19], 15, v[18:19]
	v_lshlrev_b64 v[20:21], 15, v[20:21]
	v_lshlrev_b64 v[30:31], 15, v[30:31]
	v_lshlrev_b64 v[26:27], 15, v[26:27]
	v_lshl_add_u64 v[2:3], v[28:29], 0, v[2:3]
	v_lshl_add_u64 v[6:7], v[28:29], 0, v[4:5]
	v_lshl_add_u64 v[10:11], v[28:29], 0, v[10:11]
	v_lshl_add_u64 v[14:15], v[28:29], 0, v[12:13]
	v_lshl_add_u64 v[18:19], v[28:29], 0, v[18:19]
	v_lshl_add_u64 v[22:23], v[28:29], 0, v[20:21]
	v_lshl_add_u64 v[30:31], v[28:29], 0, v[30:31]
	v_lshl_add_u64 v[32:33], v[28:29], 0, v[26:27]
	global_load_dwordx4 v[2:5], v[2:3], off nt
	s_nop 0
	global_load_dwordx4 v[6:9], v[6:7], off nt
	s_nop 0
	global_load_dwordx4 v[10:13], v[10:11], off nt
	s_nop 0
	global_load_dwordx4 v[14:17], v[14:15], off nt
	s_nop 0
	global_load_dwordx4 v[18:21], v[18:19], off nt
	s_nop 0
	global_load_dwordx4 v[22:25], v[22:23], off nt
	s_nop 0
	global_load_dwordx4 v[26:29], v[30:31], off nt
	s_nop 0
	global_load_dwordx4 v[30:33], v[32:33], off nt
	s_branch .LBB0_10

.LBB0_16:
	s_or_b64 exec, exec, s[10:11]
	v_readlane_b32 s16, v242, 31
	s_cmpk_gt_i32 s56, 0x21ff
	v_readlane_b32 s17, v242, 32
	v_readlane_b32 s18, v242, 33
	v_readlane_b32 s19, v242, 34
	v_readlane_b32 s26, v242, 41
	v_readlane_b32 s27, v242, 42
	v_readlane_b32 s20, v242, 35
	v_readlane_b32 s21, v242, 36
	v_readlane_b32 s22, v242, 37
	v_readlane_b32 s23, v242, 38
	v_readlane_b32 s24, v242, 39
	v_readlane_b32 s25, v242, 40
	v_readlane_b32 s28, v242, 43
	v_readlane_b32 s29, v242, 44
	v_readlane_b32 s30, v242, 45
	v_readlane_b32 s31, v242, 46
	s_cbranch_scc1 .LBB0_22
	v_lshlrev_b32_e32 v216, 4, v142
	v_add_u32_e32 v217, 0x1000, v216
	v_mov_b32_e32 v218, 0x358637bd
	v_xor_b32_e32 v130, 1, v142
	v_lshlrev_b32_e32 v208, 2, v130
	v_xor_b32_e32 v130, 2, v142
	v_lshlrev_b32_e32 v209, 2, v130
	v_xor_b32_e32 v130, 4, v142
	v_lshlrev_b32_e32 v210, 2, v130
	v_xor_b32_e32 v130, 8, v142
	v_lshlrev_b32_e32 v211, 2, v130
	v_xor_b32_e32 v130, 16, v142
	v_lshlrev_b32_e32 v212, 2, v130
	v_xor_b32_e32 v130, 32, v142
	v_lshlrev_b32_e32 v213, 2, v130
	global_load_dwordx4 v[2:5], v216, s[26:27] offset:0 nt
	global_load_dwordx4 v[6:9], v216, s[26:27] offset:1024 nt
	global_load_dwordx4 v[10:13], v216, s[26:27] offset:2048 nt
	global_load_dwordx4 v[14:17], v216, s[26:27] offset:3072 nt
	global_load_dwordx4 v[18:21], v217, s[26:27] offset:0 nt
	global_load_dwordx4 v[22:25], v217, s[26:27] offset:1024 nt
	global_load_dwordx4 v[26:29], v217, s[26:27] offset:2048 nt
	global_load_dwordx4 v[30:33], v217, s[26:27] offset:3072 nt
	s_ashr_i32 s57, s56, 31
	s_lshl_b64 s[0:1], s[56:57], 13
	s_add_u32 s8, s16, s0
	s_addc_u32 s9, s17, s1
	global_load_dwordx4 v[34:37], v216, s[8:9] offset:0 nt
	global_load_dwordx4 v[38:41], v216, s[8:9] offset:1024 nt
	global_load_dwordx4 v[42:45], v216, s[8:9] offset:2048 nt
	global_load_dwordx4 v[46:49], v216, s[8:9] offset:3072 nt
	global_load_dwordx4 v[50:53], v217, s[8:9] offset:0 nt
	global_load_dwordx4 v[54:57], v217, s[8:9] offset:1024 nt
	global_load_dwordx4 v[58:61], v217, s[8:9] offset:2048 nt
	global_load_dwordx4 v[62:65], v217, s[8:9] offset:3072 nt
	s_add_u32 s8, s8, 0x1000000
	s_addc_u32 s9, s9, 0
	global_load_dwordx4 v[66:69], v216, s[8:9] offset:0 nt
	global_load_dwordx4 v[70:73], v216, s[8:9] offset:1024 nt
	global_load_dwordx4 v[74:77], v216, s[8:9] offset:2048 nt
	global_load_dwordx4 v[78:81], v216, s[8:9] offset:3072 nt
	global_load_dwordx4 v[82:85], v217, s[8:9] offset:0 nt
	global_load_dwordx4 v[86:89], v217, s[8:9] offset:1024 nt
	global_load_dwordx4 v[90:93], v217, s[8:9] offset:2048 nt
	global_load_dwordx4 v[94:97], v217, s[8:9] offset:3072 nt
	s_add_u32 s8, s8, 0x1000000
	s_addc_u32 s9, s9, 0
	global_load_dwordx4 v[98:101], v216, s[8:9] offset:0 nt
	global_load_dwordx4 v[102:105], v216, s[8:9] offset:1024 nt
	global_load_dwordx4 v[106:109], v216, s[8:9] offset:2048 nt
	global_load_dwordx4 v[110:113], v216, s[8:9] offset:3072 nt
	global_load_dwordx4 v[114:117], v217, s[8:9] offset:0 nt
	global_load_dwordx4 v[118:121], v217, s[8:9] offset:1024 nt
	global_load_dwordx4 v[122:125], v217, s[8:9] offset:2048 nt
	global_load_dwordx4 v[126:129], v217, s[8:9] offset:3072 nt
	s_add_u32 s8, s8, 0x1000000
	s_addc_u32 s9, s9, 0
	global_load_dwordx4 v[144:147], v216, s[8:9] offset:0 nt
	global_load_dwordx4 v[148:151], v216, s[8:9] offset:1024 nt
	global_load_dwordx4 v[152:155], v216, s[8:9] offset:2048 nt
	global_load_dwordx4 v[156:159], v216, s[8:9] offset:3072 nt
	global_load_dwordx4 v[160:163], v217, s[8:9] offset:0 nt
	global_load_dwordx4 v[164:167], v217, s[8:9] offset:1024 nt
	global_load_dwordx4 v[168:171], v217, s[8:9] offset:2048 nt
	global_load_dwordx4 v[172:175], v217, s[8:9] offset:3072 nt
	s_cmpk_gt_i32 s56, 0x1ff
	s_cbranch_scc1 .Lp0r_no5
	s_add_u32 s8, s18, s0
	s_addc_u32 s9, s19, s1
	global_load_dwordx4 v[176:179], v216, s[8:9] offset:0 nt
	global_load_dwordx4 v[180:183], v216, s[8:9] offset:1024 nt
	global_load_dwordx4 v[184:187], v216, s[8:9] offset:2048 nt
	global_load_dwordx4 v[188:191], v216, s[8:9] offset:3072 nt
	global_load_dwordx4 v[192:195], v217, s[8:9] offset:0 nt
	global_load_dwordx4 v[196:199], v217, s[8:9] offset:1024 nt
	global_load_dwordx4 v[200:203], v217, s[8:9] offset:2048 nt
	global_load_dwordx4 v[204:207], v217, s[8:9] offset:3072 nt
